# v025 + general attention tile body trimmed: 16 counted LDS waits merged to 3, one-sided mask blocks with pipelined compares
# speedup vs baseline: 1.0158x; 1.0043x over previous
; DI void attn_unit(LAS unsigned char* lds, const Args& a, int bg, int qt) {
;     ...
;         bool need_mask, col_en = true; int lo_b = -1, hi_b = 63;
;         if (is_sel) { need_mask = (j == qt); if (j == qt) hi_b = qloc; col_en = ((mask_q >> j) & 1u) != 0u; }
;         else { need_mask = (j == qt) || (j == qt - 8); if (j == qt) hi_b = qloc; if (j == qt - 8) lo_b = qloc; }
.Lat_nosel_5:
	s_cmp_eq_u32 s98, s73
	s_cselect_b32 s8, 1, 0
	s_cmp_eq_u32 s98, s20
	s_cselect_b32 s9, 1, 0
	s_andn2_b32 s9, s9, s6
	s_lshl_b32 s10, s9, 1
	s_or_b32 s5, s8, s10
	s_cmp_eq_u32 s5, 0
	s_cbranch_scc1 .Lat_nomask_6
	v_mov_b32_e32 v120, 63
	v_mov_b32_e32 v121, -1
	s_cmp_eq_u32 s8, 1
	s_cselect_b64 s[10:11], -1, 0
	s_cmp_eq_u32 s9, 1
	s_cselect_b64 s[8:9], -1, 0
	v_cndmask_b32_e64 v120, v120, v253, s[10:11]
	v_cndmask_b32_e64 v121, v121, v253, s[8:9]
	v_sub_u32_e32 v120, v120, v243
	v_sub_u32_e32 v121, v121, v243

; #define LAS __attribute__((address_space(3)))
; #define MFMA32(a, b, c) __builtin_amdgcn_mfma_f32_32x32x16_bf16((a), (b), (c), 0, 0, 0)
; DI void attn_tile(LAS const unsigned char* Ks, LAS const unsigned char* VT, const bf16x8 (&qf)[4], int ql, int hi,
;                   bool need_mask, bool col_en, int lo_b, int hi_b, float& m_ref, float& l_run, f32x16 (&o)[2], f32x16 (&sp)[2]) {
;     ...
;         bf16x8 kf[4];
; #pragma unroll
;         for (int d0 = 0; d0 < 4; ++d0) { const int c = 2 * d0 + hi; kf[d0] = *(LAS const bf16x8*)(Ks + c * 1024 + ((ql + 32 * p) << 4)); }
;         f32x16 acc;
;         if (plain) {
; #pragma unroll
;             for (int r = 0; r < 16; ++r) acc[r] = 0.f;
; #pragma unroll
;             for (int d0 = 0; d0 < 4; ++d0) acc = MFMA32(kf[d0], qf[d0], acc);
.Lat_qkgo_8:
	s_waitcnt lgkmcnt(1)
	s_cmp_eq_u32 s7, 1
	s_cbranch_scc0 .Lat_c0s_9
	v_mfma_f32_32x32x16_bf16 v[50:65], v[84:87], v[66:69], 0
	s_branch .Lat_c0j_10

; #define MFMA32(a, b, c) __builtin_amdgcn_mfma_f32_32x32x16_bf16((a), (b), (c), 0, 0, 0)
; DI void attn_tile(LAS const unsigned char* Ks, LAS const unsigned char* VT, const bf16x8 (&qf)[4], int ql, int hi,
;                   bool need_mask, bool col_en, int lo_b, int hi_b, float& m_ref, float& l_run, f32x16 (&o)[2], f32x16 (&sp)[2]) {
;     ...
;             for (int d0 = 0; d0 < 4; ++d0) acc = MFMA32(kf[d0], qf[d0], acc);
;         } else {
; #pragma unroll
;             for (int r = 0; r < 16; ++r) acc[r] = bias;
; #pragma unroll
;             for (int d0 = 0; d0 < 4; ++d0) acc = MFMA32(kf[d0], qf[d0], acc);
.Lat_c0j_10:
	v_mfma_f32_32x32x16_bf16 v[50:65], v[88:91], v[70:73], v[50:65]
	v_mfma_f32_32x32x16_bf16 v[50:65], v[92:95], v[74:77], v[50:65]
	v_mfma_f32_32x32x16_bf16 v[50:65], v[96:99], v[78:81], v[50:65]
	s_cmp_eq_u32 s7, 1
	s_cbranch_scc0 .Lat_c0s_11
	v_mfma_f32_32x32x16_bf16 v[34:49], v[100:103], v[66:69], 0
	s_branch .Lat_c0j_12

; DI void attn_tile(LAS const unsigned char* Ks, LAS const unsigned char* VT, const bf16x8 (&qf)[4], int ql, int hi,
;                   bool need_mask, bool col_en, int lo_b, int hi_b, float& m_ref, float& l_run, f32x16 (&o)[2], f32x16 (&sp)[2]) {
;     ...
;     if (need_mask) {
; #pragma unroll
;         for (int p = 0; p < 2; ++p)
; #pragma unroll
;             for (int r = 0; r < 16; ++r) { const int kvl = 32 * p + (r & 3) + 8 * (r >> 2) + 4 * hi; const bool ok = (kvl <= hi_b) && (kvl > lo_b); sp[p][r] = ok ? sp[p][r] : -INFINITY; }
;     }
.Lat_c0j_12:
	v_mfma_f32_32x32x16_bf16 v[34:49], v[104:107], v[70:73], v[34:49]
	v_mfma_f32_32x32x16_bf16 v[34:49], v[108:111], v[74:77], v[34:49]
	v_mfma_f32_32x32x16_bf16 v[34:49], v[112:115], v[78:81], v[34:49]
	s_cmp_eq_u32 s5, 0
	s_cbranch_scc1 .Lat_nomask2_13
	s_nop 7
	s_nop 7
	s_cmp_eq_u32 s5, 1
	s_cbranch_scc0 .Lat_masklo_14
	v_cmp_le_i32_e64 s[8:9], 0, v120
	v_cmp_le_i32_e64 s[10:11], 1, v120
	v_cmp_le_i32_e64 vcc, 2, v120
	v_cndmask_b32_e64 v50, v242, v50, s[8:9]
	v_cmp_le_i32_e64 s[8:9], 3, v120
	v_cndmask_b32_e64 v51, v242, v51, s[10:11]
	v_cmp_le_i32_e64 s[10:11], 8, v120
	v_cndmask_b32_e64 v52, v242, v52, vcc
	v_cmp_le_i32_e64 vcc, 9, v120
	v_cndmask_b32_e64 v53, v242, v53, s[8:9]
	v_cmp_le_i32_e64 s[8:9], 10, v120
	v_cndmask_b32_e64 v54, v242, v54, s[10:11]
	v_cmp_le_i32_e64 s[10:11], 11, v120
	v_cndmask_b32_e64 v55, v242, v55, vcc
	v_cmp_le_i32_e64 vcc, 16, v120
	v_cndmask_b32_e64 v56, v242, v56, s[8:9]
	v_cmp_le_i32_e64 s[8:9], 17, v120
	v_cndmask_b32_e64 v57, v242, v57, s[10:11]
	v_cmp_le_i32_e64 s[10:11], 18, v120
	v_cndmask_b32_e64 v58, v242, v58, vcc
	v_cmp_le_i32_e64 vcc, 19, v120
	v_cndmask_b32_e64 v59, v242, v59, s[8:9]
	v_cmp_le_i32_e64 s[8:9], 24, v120
	v_cndmask_b32_e64 v60, v242, v60, s[10:11]
	v_cmp_le_i32_e64 s[10:11], 25, v120
	v_cndmask_b32_e64 v61, v242, v61, vcc
	v_cmp_le_i32_e64 vcc, 26, v120
	v_cndmask_b32_e64 v62, v242, v62, s[8:9]
	v_cmp_le_i32_e64 s[8:9], 27, v120
	v_cndmask_b32_e64 v63, v242, v63, s[10:11]
	v_cmp_le_i32_e64 s[10:11], 32, v120
	v_cndmask_b32_e64 v64, v242, v64, vcc
	v_cmp_le_i32_e64 vcc, 33, v120
	v_cndmask_b32_e64 v65, v242, v65, s[8:9]
	v_cmp_le_i32_e64 s[8:9], 34, v120
	v_cndmask_b32_e64 v34, v242, v34, s[10:11]
	v_cmp_le_i32_e64 s[10:11], 35, v120
	v_cndmask_b32_e64 v35, v242, v35, vcc
	v_cmp_le_i32_e64 vcc, 40, v120
	v_cndmask_b32_e64 v36, v242, v36, s[8:9]
	v_cmp_le_i32_e64 s[8:9], 41, v120
	v_cndmask_b32_e64 v37, v242, v37, s[10:11]
	v_cmp_le_i32_e64 s[10:11], 42, v120
	v_cndmask_b32_e64 v38, v242, v38, vcc
	v_cmp_le_i32_e64 vcc, 43, v120
	v_cndmask_b32_e64 v39, v242, v39, s[8:9]
	v_cmp_le_i32_e64 s[8:9], 48, v120
	v_cndmask_b32_e64 v40, v242, v40, s[10:11]
	v_cmp_le_i32_e64 s[10:11], 49, v120
	v_cndmask_b32_e64 v41, v242, v41, vcc
	v_cmp_le_i32_e64 vcc, 50, v120
	v_cndmask_b32_e64 v42, v242, v42, s[8:9]
	v_cmp_le_i32_e64 s[8:9], 51, v120
	v_cndmask_b32_e64 v43, v242, v43, s[10:11]
	v_cmp_le_i32_e64 s[10:11], 56, v120
	v_cndmask_b32_e64 v44, v242, v44, vcc
	v_cmp_le_i32_e64 vcc, 57, v120
	v_cndmask_b32_e64 v45, v242, v45, s[8:9]
	v_cmp_le_i32_e64 s[8:9], 58, v120
	v_cndmask_b32_e64 v46, v242, v46, s[10:11]
	v_cmp_le_i32_e64 s[10:11], 59, v120
	v_cndmask_b32_e64 v47, v242, v47, vcc
	v_cndmask_b32_e64 v48, v242, v48, s[8:9]
	v_cndmask_b32_e64 v49, v242, v49, s[10:11]
	s_branch .Lat_nomask2_13
.Lat_masklo_14:
	s_cmp_eq_u32 s5, 2
	s_cbranch_scc0 .Lat_maskboth_15
	v_cmp_gt_i32_e64 s[8:9], 0, v121
	v_cmp_gt_i32_e64 s[10:11], 1, v121
	v_cmp_gt_i32_e64 vcc, 2, v121
	v_cndmask_b32_e64 v50, v242, v50, s[8:9]
	v_cmp_gt_i32_e64 s[8:9], 3, v121
	v_cndmask_b32_e64 v51, v242, v51, s[10:11]
	v_cmp_gt_i32_e64 s[10:11], 8, v121
	v_cndmask_b32_e64 v52, v242, v52, vcc
	v_cmp_gt_i32_e64 vcc, 9, v121
	v_cndmask_b32_e64 v53, v242, v53, s[8:9]
	v_cmp_gt_i32_e64 s[8:9], 10, v121
	v_cndmask_b32_e64 v54, v242, v54, s[10:11]
	v_cmp_gt_i32_e64 s[10:11], 11, v121
	v_cndmask_b32_e64 v55, v242, v55, vcc
	v_cmp_gt_i32_e64 vcc, 16, v121
	v_cndmask_b32_e64 v56, v242, v56, s[8:9]
	v_cmp_gt_i32_e64 s[8:9], 17, v121
	v_cndmask_b32_e64 v57, v242, v57, s[10:11]
	v_cmp_gt_i32_e64 s[10:11], 18, v121
	v_cndmask_b32_e64 v58, v242, v58, vcc
	v_cmp_gt_i32_e64 vcc, 19, v121
	v_cndmask_b32_e64 v59, v242, v59, s[8:9]
	v_cmp_gt_i32_e64 s[8:9], 24, v121
	v_cndmask_b32_e64 v60, v242, v60, s[10:11]
	v_cmp_gt_i32_e64 s[10:11], 25, v121
	v_cndmask_b32_e64 v61, v242, v61, vcc
	v_cmp_gt_i32_e64 vcc, 26, v121
	v_cndmask_b32_e64 v62, v242, v62, s[8:9]
	v_cmp_gt_i32_e64 s[8:9], 27, v121
	v_cndmask_b32_e64 v63, v242, v63, s[10:11]
	v_cmp_gt_i32_e64 s[10:11], 32, v121
	v_cndmask_b32_e64 v64, v242, v64, vcc
	v_cmp_gt_i32_e64 vcc, 33, v121
	v_cndmask_b32_e64 v65, v242, v65, s[8:9]
	v_cmp_gt_i32_e64 s[8:9], 34, v121
	v_cndmask_b32_e64 v34, v242, v34, s[10:11]
	v_cmp_gt_i32_e64 s[10:11], 35, v121
	v_cndmask_b32_e64 v35, v242, v35, vcc
	v_cmp_gt_i32_e64 vcc, 40, v121
	v_cndmask_b32_e64 v36, v242, v36, s[8:9]
	v_cmp_gt_i32_e64 s[8:9], 41, v121
	v_cndmask_b32_e64 v37, v242, v37, s[10:11]
	v_cmp_gt_i32_e64 s[10:11], 42, v121
	v_cndmask_b32_e64 v38, v242, v38, vcc
	v_cmp_gt_i32_e64 vcc, 43, v121
	v_cndmask_b32_e64 v39, v242, v39, s[8:9]
	v_cmp_gt_i32_e64 s[8:9], 48, v121
	v_cndmask_b32_e64 v40, v242, v40, s[10:11]
	v_cmp_gt_i32_e64 s[10:11], 49, v121
	v_cndmask_b32_e64 v41, v242, v41, vcc
	v_cmp_gt_i32_e64 vcc, 50, v121
	v_cndmask_b32_e64 v42, v242, v42, s[8:9]
	v_cmp_gt_i32_e64 s[8:9], 51, v121
	v_cndmask_b32_e64 v43, v242, v43, s[10:11]
	v_cmp_gt_i32_e64 s[10:11], 56, v121
	v_cndmask_b32_e64 v44, v242, v44, vcc
	v_cmp_gt_i32_e64 vcc, 57, v121
	v_cndmask_b32_e64 v45, v242, v45, s[8:9]
	v_cmp_gt_i32_e64 s[8:9], 58, v121
	v_cndmask_b32_e64 v46, v242, v46, s[10:11]
	v_cmp_gt_i32_e64 s[10:11], 59, v121
	v_cndmask_b32_e64 v47, v242, v47, vcc
	v_cndmask_b32_e64 v48, v242, v48, s[8:9]
	v_cndmask_b32_e64 v49, v242, v49, s[10:11]
	s_branch .Lat_nomask2_13
; DI void attn_tile(LAS const unsigned char* Ks, LAS const unsigned char* VT, const bf16x8 (&qf)[4], int ql, int hi,
;                   bool need_mask, bool col_en, int lo_b, int hi_b, float& m_ref, float& l_run, f32x16 (&o)[2], f32x16 (&sp)[2]) {
;     ...
;             for (int r = 0; r < 16; ++r) { const int kvl = 32 * p + (r & 3) + 8 * (r >> 2) + 4 * hi; const bool ok = (kvl <= hi_b) && (kvl > lo_b); sp[p][r] = ok ? sp[p][r] : -INFINITY; }
.Lat_maskboth_15:
	v_cmp_le_i32_e32 vcc, 0, v120
	v_cmp_gt_i32_e64 s[8:9], 0, v121
	s_and_b64 vcc, s[8:9], vcc
	v_cndmask_b32_e32 v50, v242, v50, vcc
	v_cmp_le_i32_e32 vcc, 1, v120
	v_cmp_gt_i32_e64 s[8:9], 1, v121
	s_and_b64 vcc, s[8:9], vcc
	v_cndmask_b32_e32 v51, v242, v51, vcc
	v_cmp_le_i32_e32 vcc, 2, v120
	v_cmp_gt_i32_e64 s[8:9], 2, v121
	s_and_b64 vcc, s[8:9], vcc
	v_cndmask_b32_e32 v52, v242, v52, vcc
	v_cmp_le_i32_e32 vcc, 3, v120
	v_cmp_gt_i32_e64 s[8:9], 3, v121
	s_and_b64 vcc, s[8:9], vcc
	v_cndmask_b32_e32 v53, v242, v53, vcc
	v_cmp_le_i32_e32 vcc, 8, v120
	v_cmp_gt_i32_e64 s[8:9], 8, v121
	s_and_b64 vcc, s[8:9], vcc
	v_cndmask_b32_e32 v54, v242, v54, vcc
	v_cmp_le_i32_e32 vcc, 9, v120
	v_cmp_gt_i32_e64 s[8:9], 9, v121
	s_and_b64 vcc, s[8:9], vcc
	v_cndmask_b32_e32 v55, v242, v55, vcc
	v_cmp_le_i32_e32 vcc, 10, v120
	v_cmp_gt_i32_e64 s[8:9], 10, v121
	s_and_b64 vcc, s[8:9], vcc
	v_cndmask_b32_e32 v56, v242, v56, vcc
	v_cmp_le_i32_e32 vcc, 11, v120
	v_cmp_gt_i32_e64 s[8:9], 11, v121
	s_and_b64 vcc, s[8:9], vcc
	v_cndmask_b32_e32 v57, v242, v57, vcc
	v_cmp_le_i32_e32 vcc, 16, v120
	v_cmp_gt_i32_e64 s[8:9], 16, v121
	s_and_b64 vcc, s[8:9], vcc
	v_cndmask_b32_e32 v58, v242, v58, vcc
	v_cmp_le_i32_e32 vcc, 17, v120
	v_cmp_gt_i32_e64 s[8:9], 17, v121
	s_and_b64 vcc, s[8:9], vcc
	v_cndmask_b32_e32 v59, v242, v59, vcc
	v_cmp_le_i32_e32 vcc, 18, v120
	v_cmp_gt_i32_e64 s[8:9], 18, v121
	s_and_b64 vcc, s[8:9], vcc
	v_cndmask_b32_e32 v60, v242, v60, vcc
	v_cmp_le_i32_e32 vcc, 19, v120
	v_cmp_gt_i32_e64 s[8:9], 19, v121
	s_and_b64 vcc, s[8:9], vcc
	v_cndmask_b32_e32 v61, v242, v61, vcc
	v_cmp_le_i32_e32 vcc, 24, v120
	v_cmp_gt_i32_e64 s[8:9], 24, v121
	s_and_b64 vcc, s[8:9], vcc
	v_cndmask_b32_e32 v62, v242, v62, vcc
	v_cmp_le_i32_e32 vcc, 25, v120
	v_cmp_gt_i32_e64 s[8:9], 25, v121
	s_and_b64 vcc, s[8:9], vcc
	v_cndmask_b32_e32 v63, v242, v63, vcc
	v_cmp_le_i32_e32 vcc, 26, v120
	v_cmp_gt_i32_e64 s[8:9], 26, v121
	s_and_b64 vcc, s[8:9], vcc
	v_cndmask_b32_e32 v64, v242, v64, vcc
	v_cmp_le_i32_e32 vcc, 27, v120
	v_cmp_gt_i32_e64 s[8:9], 27, v121
	s_and_b64 vcc, s[8:9], vcc
	v_cndmask_b32_e32 v65, v242, v65, vcc
	v_cmp_le_i32_e32 vcc, 32, v120
	v_cmp_gt_i32_e64 s[8:9], 32, v121
	s_and_b64 vcc, s[8:9], vcc
	v_cndmask_b32_e32 v34, v242, v34, vcc
	v_cmp_le_i32_e32 vcc, 33, v120
	v_cmp_gt_i32_e64 s[8:9], 33, v121
	s_and_b64 vcc, s[8:9], vcc
	v_cndmask_b32_e32 v35, v242, v35, vcc
	v_cmp_le_i32_e32 vcc, 34, v120
	v_cmp_gt_i32_e64 s[8:9], 34, v121
	s_and_b64 vcc, s[8:9], vcc
	v_cndmask_b32_e32 v36, v242, v36, vcc
	v_cmp_le_i32_e32 vcc, 35, v120
	v_cmp_gt_i32_e64 s[8:9], 35, v121
	s_and_b64 vcc, s[8:9], vcc
	v_cndmask_b32_e32 v37, v242, v37, vcc
	v_cmp_le_i32_e32 vcc, 40, v120
	v_cmp_gt_i32_e64 s[8:9], 40, v121
	s_and_b64 vcc, s[8:9], vcc
	v_cndmask_b32_e32 v38, v242, v38, vcc
	v_cmp_le_i32_e32 vcc, 41, v120
	v_cmp_gt_i32_e64 s[8:9], 41, v121
	s_and_b64 vcc, s[8:9], vcc
	v_cndmask_b32_e32 v39, v242, v39, vcc
	v_cmp_le_i32_e32 vcc, 42, v120
	v_cmp_gt_i32_e64 s[8:9], 42, v121
	s_and_b64 vcc, s[8:9], vcc
	v_cndmask_b32_e32 v40, v242, v40, vcc
	v_cmp_le_i32_e32 vcc, 43, v120
	v_cmp_gt_i32_e64 s[8:9], 43, v121
	s_and_b64 vcc, s[8:9], vcc
	v_cndmask_b32_e32 v41, v242, v41, vcc
	v_cmp_le_i32_e32 vcc, 48, v120
	v_cmp_gt_i32_e64 s[8:9], 48, v121
	s_and_b64 vcc, s[8:9], vcc
	v_cndmask_b32_e32 v42, v242, v42, vcc
	v_cmp_le_i32_e32 vcc, 49, v120
	v_cmp_gt_i32_e64 s[8:9], 49, v121
	s_and_b64 vcc, s[8:9], vcc
	v_cndmask_b32_e32 v43, v242, v43, vcc
	v_cmp_le_i32_e32 vcc, 50, v120
	v_cmp_gt_i32_e64 s[8:9], 50, v121
	s_and_b64 vcc, s[8:9], vcc
	v_cndmask_b32_e32 v44, v242, v44, vcc
	v_cmp_le_i32_e32 vcc, 51, v120
	v_cmp_gt_i32_e64 s[8:9], 51, v121
	s_and_b64 vcc, s[8:9], vcc
	v_cndmask_b32_e32 v45, v242, v45, vcc
	v_cmp_le_i32_e32 vcc, 56, v120
	v_cmp_gt_i32_e64 s[8:9], 56, v121
	s_and_b64 vcc, s[8:9], vcc
	v_cndmask_b32_e32 v46, v242, v46, vcc
	v_cmp_le_i32_e32 vcc, 57, v120
	v_cmp_gt_i32_e64 s[8:9], 57, v121
	s_and_b64 vcc, s[8:9], vcc
	v_cndmask_b32_e32 v47, v242, v47, vcc
	v_cmp_le_i32_e32 vcc, 58, v120
	v_cmp_gt_i32_e64 s[8:9], 58, v121
	s_and_b64 vcc, s[8:9], vcc
	v_cndmask_b32_e32 v48, v242, v48, vcc
	v_cmp_le_i32_e32 vcc, 59, v120
	v_cmp_gt_i32_e64 s[8:9], 59, v121
	s_and_b64 vcc, s[8:9], vcc
	v_cndmask_b32_e32 v49, v242, v49, vcc

; #define LAS __attribute__((address_space(3)))
; #define MFMA32(a, b, c) __builtin_amdgcn_mfma_f32_32x32x16_bf16((a), (b), (c), 0, 0, 0)
; DI void attn_tile(LAS const unsigned char* Ks, LAS const unsigned char* VT, const bf16x8 (&qf)[4], int ql, int hi,
;                   bool need_mask, bool col_en, int lo_b, int hi_b, float& m_ref, float& l_run, f32x16 (&o)[2], f32x16 (&sp)[2]) {
;     ...
;         for (int d0 = 0; d0 < 4; ++d0) { const int c = 2 * d0 + hi; kf[d0] = *(LAS const bf16x8*)(Ks + c * 1024 + ((ql + 32 * p) << 4)); }
;         f32x16 acc;
;         if (plain) {
; #pragma unroll
;             for (int r = 0; r < 16; ++r) acc[r] = 0.f;
; #pragma unroll
;             for (int d0 = 0; d0 < 4; ++d0) acc = MFMA32(kf[d0], qf[d0], acc);
;         } else {
; #pragma unroll
;             for (int r = 0; r < 16; ++r) acc[r] = bias;
; #pragma unroll
;             for (int d0 = 0; d0 < 4; ++d0) acc = MFMA32(kf[d0], qf[d0], acc);
;     ...
;             const s16x4 lo = __builtin_bit_cast(s16x4, __builtin_amdgcn_ds_read_tr16_b64_v4i16((LAS v4i16_t*)(vb + dh * 4096 + ks * 1024)));
;             const s16x4 hh = __builtin_bit_cast(s16x4, __builtin_amdgcn_ds_read_tr16_b64_v4i16((LAS v4i16_t*)(vb + dh * 4096 + ks * 1024 + 512)));
.Lat_c0j_30:
	ds_read_b64_tr_b16 v[192:193], v126 offset:8192
	ds_read_b64_tr_b16 v[194:195], v126 offset:8704
	v_mfma_f32_32x32x16_bf16 v[50:65], v[88:91], v[70:73], v[50:65]
	ds_read_b64_tr_b16 v[208:209], v126 offset:12288
	ds_read_b64_tr_b16 v[210:211], v126 offset:12800
	v_mfma_f32_32x32x16_bf16 v[50:65], v[92:95], v[74:77], v[50:65]
	ds_read_b64_tr_b16 v[196:197], v126 offset:9216
	ds_read_b64_tr_b16 v[198:199], v126 offset:9728
	v_mfma_f32_32x32x16_bf16 v[50:65], v[96:99], v[78:81], v[50:65]
	ds_read_b64_tr_b16 v[212:213], v126 offset:13312
	ds_read_b64_tr_b16 v[214:215], v126 offset:13824
	s_cmp_eq_u32 s7, 1
	s_cbranch_scc0 .Lat_c0s_31
	v_mfma_f32_32x32x16_bf16 v[34:49], v[100:103], v[66:69], 0
	s_branch .Lat_c0j_32

; #define LAS __attribute__((address_space(3)))
; #define MFMA32(a, b, c) __builtin_amdgcn_mfma_f32_32x32x16_bf16((a), (b), (c), 0, 0, 0)
; DI void attn_tile(LAS const unsigned char* Ks, LAS const unsigned char* VT, const bf16x8 (&qf)[4], int ql, int hi,
;                   bool need_mask, bool col_en, int lo_b, int hi_b, float& m_ref, float& l_run, f32x16 (&o)[2], f32x16 (&sp)[2]) {
;     ...
;     if (need_mask) {
; #pragma unroll
;         for (int p = 0; p < 2; ++p)
; #pragma unroll
;             for (int r = 0; r < 16; ++r) { const int kvl = 32 * p + (r & 3) + 8 * (r >> 2) + 4 * hi; const bool ok = (kvl <= hi_b) && (kvl > lo_b); sp[p][r] = ok ? sp[p][r] : -INFINITY; }
;     }
;     ...
;             const s16x4 lo = __builtin_bit_cast(s16x4, __builtin_amdgcn_ds_read_tr16_b64_v4i16((LAS v4i16_t*)(vb + dh * 4096 + ks * 1024)));
;             const s16x4 hh = __builtin_bit_cast(s16x4, __builtin_amdgcn_ds_read_tr16_b64_v4i16((LAS v4i16_t*)(vb + dh * 4096 + ks * 1024 + 512)));
;             vf[ks] = (bf16x8){lo[0], lo[1], lo[2], lo[3], hh[0], hh[1], hh[2], hh[3]};
;         }
; #pragma unroll
;         for (int ks = 0; ks < 4; ++ks) o[dh] = MFMA32(vf[ks], pk[ks >> 1][ks & 1], o[dh]);
.Lat_c0j_32:
	ds_read_b64_tr_b16 v[200:201], v126 offset:10240
	ds_read_b64_tr_b16 v[202:203], v126 offset:10752
	v_mfma_f32_32x32x16_bf16 v[34:49], v[104:107], v[70:73], v[34:49]
	ds_read_b64_tr_b16 v[216:217], v126 offset:14336
	ds_read_b64_tr_b16 v[218:219], v126 offset:14848
	v_mfma_f32_32x32x16_bf16 v[34:49], v[108:111], v[74:77], v[34:49]
	ds_read_b64_tr_b16 v[204:205], v126 offset:11264
	ds_read_b64_tr_b16 v[206:207], v126 offset:11776
	v_mfma_f32_32x32x16_bf16 v[34:49], v[112:115], v[78:81], v[34:49]
	ds_read_b64_tr_b16 v[220:221], v126 offset:15360
	ds_read_b64_tr_b16 v[222:223], v126 offset:15872
	s_waitcnt lgkmcnt(8)
	v_mfma_f32_32x32x16_bf16 v[18:33], v[192:195], v[224:227], v[18:33]
	v_mfma_f32_32x32x16_bf16 v[2:17], v[208:211], v[224:227], v[2:17]
	v_mfma_f32_32x32x16_bf16 v[18:33], v[196:199], v[228:231], v[18:33]
	v_mfma_f32_32x32x16_bf16 v[2:17], v[212:215], v[228:231], v[2:17]
	s_cmp_eq_u32 s5, 0
	s_cbranch_scc1 .Lat_nomask2_33
	s_nop 7
	s_nop 7
	s_cmp_eq_u32 s5, 1
	s_cbranch_scc0 .Lat_masklo_34
	v_cmp_le_i32_e64 s[8:9], 0, v120
	v_cmp_le_i32_e64 s[10:11], 1, v120
	v_cmp_le_i32_e64 vcc, 2, v120
	v_cndmask_b32_e64 v50, v242, v50, s[8:9]
	v_cmp_le_i32_e64 s[8:9], 3, v120
	v_cndmask_b32_e64 v51, v242, v51, s[10:11]
	v_cmp_le_i32_e64 s[10:11], 8, v120
	v_cndmask_b32_e64 v52, v242, v52, vcc
	v_cmp_le_i32_e64 vcc, 9, v120
	v_cndmask_b32_e64 v53, v242, v53, s[8:9]
	v_cmp_le_i32_e64 s[8:9], 10, v120
	v_cndmask_b32_e64 v54, v242, v54, s[10:11]
	v_cmp_le_i32_e64 s[10:11], 11, v120
	v_cndmask_b32_e64 v55, v242, v55, vcc
	v_cmp_le_i32_e64 vcc, 16, v120
	v_cndmask_b32_e64 v56, v242, v56, s[8:9]
	v_cmp_le_i32_e64 s[8:9], 17, v120
	v_cndmask_b32_e64 v57, v242, v57, s[10:11]
	v_cmp_le_i32_e64 s[10:11], 18, v120
	v_cndmask_b32_e64 v58, v242, v58, vcc
	v_cmp_le_i32_e64 vcc, 19, v120
	v_cndmask_b32_e64 v59, v242, v59, s[8:9]
	v_cmp_le_i32_e64 s[8:9], 24, v120
	v_cndmask_b32_e64 v60, v242, v60, s[10:11]
	v_cmp_le_i32_e64 s[10:11], 25, v120
	v_cndmask_b32_e64 v61, v242, v61, vcc
	v_cmp_le_i32_e64 vcc, 26, v120
	v_cndmask_b32_e64 v62, v242, v62, s[8:9]
	v_cmp_le_i32_e64 s[8:9], 27, v120
	v_cndmask_b32_e64 v63, v242, v63, s[10:11]
	v_cmp_le_i32_e64 s[10:11], 32, v120
	v_cndmask_b32_e64 v64, v242, v64, vcc
	v_cmp_le_i32_e64 vcc, 33, v120
	v_cndmask_b32_e64 v65, v242, v65, s[8:9]
	v_cmp_le_i32_e64 s[8:9], 34, v120
	v_cndmask_b32_e64 v34, v242, v34, s[10:11]
	v_cmp_le_i32_e64 s[10:11], 35, v120
	v_cndmask_b32_e64 v35, v242, v35, vcc
	v_cmp_le_i32_e64 vcc, 40, v120
	v_cndmask_b32_e64 v36, v242, v36, s[8:9]
	v_cmp_le_i32_e64 s[8:9], 41, v120
	v_cndmask_b32_e64 v37, v242, v37, s[10:11]
	v_cmp_le_i32_e64 s[10:11], 42, v120
	v_cndmask_b32_e64 v38, v242, v38, vcc
	v_cmp_le_i32_e64 vcc, 43, v120
	v_cndmask_b32_e64 v39, v242, v39, s[8:9]
	v_cmp_le_i32_e64 s[8:9], 48, v120
	v_cndmask_b32_e64 v40, v242, v40, s[10:11]
	v_cmp_le_i32_e64 s[10:11], 49, v120
	v_cndmask_b32_e64 v41, v242, v41, vcc
	v_cmp_le_i32_e64 vcc, 50, v120
	v_cndmask_b32_e64 v42, v242, v42, s[8:9]
	v_cmp_le_i32_e64 s[8:9], 51, v120
	v_cndmask_b32_e64 v43, v242, v43, s[10:11]
	v_cmp_le_i32_e64 s[10:11], 56, v120
	v_cndmask_b32_e64 v44, v242, v44, vcc
	v_cmp_le_i32_e64 vcc, 57, v120
	v_cndmask_b32_e64 v45, v242, v45, s[8:9]
	v_cmp_le_i32_e64 s[8:9], 58, v120
	v_cndmask_b32_e64 v46, v242, v46, s[10:11]
	v_cmp_le_i32_e64 s[10:11], 59, v120
	v_cndmask_b32_e64 v47, v242, v47, vcc
	v_cndmask_b32_e64 v48, v242, v48, s[8:9]
	v_cndmask_b32_e64 v49, v242, v49, s[10:11]
	s_branch .Lat_nomask2_33

; #define LAS __attribute__((address_space(3)))
; DI unsigned pk2(float lo, float hi) { f32x2_t v = {lo, hi}; bf16x2_t b = __builtin_convertvector(v, bf16x2_t); return __builtin_bit_cast(unsigned, b); }
; DI float fast_exp2(float x) { return __builtin_amdgcn_exp2f(x); }
; #define MFMA32(a, b, c) __builtin_amdgcn_mfma_f32_32x32x16_bf16((a), (b), (c), 0, 0, 0)
; DI void attn_tile(LAS const unsigned char* Ks, LAS const unsigned char* VT, const bf16x8 (&qf)[4], int ql, int hi,
;                   bool need_mask, bool col_en, int lo_b, int hi_b, float& m_ref, float& l_run, f32x16 (&o)[2], f32x16 (&sp)[2]) {
;     ...
;     f32x2_t ps = {0.f, 0.f};
; #pragma unroll
;     for (int r = 0; r < 16; ++r) { const float e0 = fast_exp2(sp[0][r]), e1 = fast_exp2(sp[1][r]); sp[0][r] = e0; sp[1][r] = e1; ps += (f32x2_t){e0, e1}; }
;     l_run += ps[0] + ps[1];
;     bf16x8 pk[2][2];
; #pragma unroll
;     for (int p = 0; p < 2; ++p)
; #pragma unroll
;         for (int s = 0; s < 2; ++s) { u32x4 w; w.x = pk2(sp[p][8 * s], sp[p][8 * s + 1]); w.y = pk2(sp[p][8 * s + 2], sp[p][8 * s + 3]); w.z = pk2(sp[p][8 * s + 4], sp[p][8 * s + 5]); w.w = pk2(sp[p][8 * s + 6], sp[p][8 * s + 7]); pk[p][s] = __builtin_bit_cast(bf16x8, w); }
;     LAS const unsigned char* vb = VT + ((lane_ >> 4) & 1) * 32 + (lane_ & 3) * 8 + (4 * hi + ((lane_ & 15) >> 2)) * 64;
; #pragma unroll
;     for (int dh = 0; dh < 2; ++dh) {
;         bf16x8 vf[4];
; #pragma unroll
;         for (int ks = 0; ks < 4; ++ks) {
;             const s16x4 lo = __builtin_bit_cast(s16x4, __builtin_amdgcn_ds_read_tr16_b64_v4i16((LAS v4i16_t*)(vb + dh * 4096 + ks * 1024)));
;             const s16x4 hh = __builtin_bit_cast(s16x4, __builtin_amdgcn_ds_read_tr16_b64_v4i16((LAS v4i16_t*)(vb + dh * 4096 + ks * 1024 + 512)));
;             vf[ks] = (bf16x8){lo[0], lo[1], lo[2], lo[3], hh[0], hh[1], hh[2], hh[3]};
;         }
; #pragma unroll
;         for (int ks = 0; ks < 4; ++ks) o[dh] = MFMA32(vf[ks], pk[ks >> 1][ks & 1], o[dh]);
.Lat_norescale_37:
	s_waitcnt lgkmcnt(0)
	v_mfma_f32_32x32x16_bf16 v[18:33], v[200:203], v[232:235], v[18:33]
	v_exp_f32_e32 v50, v50
	v_exp_f32_e32 v51, v51
	v_exp_f32_e32 v52, v52
	v_exp_f32_e32 v53, v53
	v_exp_f32_e32 v54, v54
	v_exp_f32_e32 v55, v55
	v_exp_f32_e32 v56, v56
	v_exp_f32_e32 v57, v57
	v_mfma_f32_32x32x16_bf16 v[2:17], v[216:219], v[232:235], v[2:17]
	v_exp_f32_e32 v58, v58
	v_exp_f32_e32 v59, v59
	v_exp_f32_e32 v60, v60
	v_exp_f32_e32 v61, v61
	v_exp_f32_e32 v62, v62
	v_exp_f32_e32 v63, v63
	v_exp_f32_e32 v64, v64
	v_exp_f32_e32 v65, v65
	v_mfma_f32_32x32x16_bf16 v[18:33], v[204:207], v[236:239], v[18:33]
	v_exp_f32_e32 v34, v34
	v_exp_f32_e32 v35, v35
	v_exp_f32_e32 v36, v36
	v_exp_f32_e32 v37, v37
	v_exp_f32_e32 v38, v38
	v_exp_f32_e32 v39, v39
	v_exp_f32_e32 v40, v40
	v_exp_f32_e32 v41, v41
	v_mfma_f32_32x32x16_bf16 v[2:17], v[220:223], v[236:239], v[2:17]
	v_exp_f32_e32 v42, v42
	v_exp_f32_e32 v43, v43
	v_exp_f32_e32 v44, v44
	v_exp_f32_e32 v45, v45
	v_exp_f32_e32 v46, v46
	v_exp_f32_e32 v47, v47
	v_exp_f32_e32 v48, v48
	v_exp_f32_e32 v49, v49
	s_waitcnt lgkmcnt(0)
	v_readfirstlane_b32 s98, v254
	v_readfirstlane_b32 s99, v255
	s_mov_b64 s[16:17], s[12:13]
	s_mov_b32 s21, s28
	s_add_i32 s77, s77, 1
	s_cmp_lt_i32 s77, s100
	s_branch .Lat_disp

; #define MFMA32(a, b, c) __builtin_amdgcn_mfma_f32_32x32x16_bf16((a), (b), (c), 0, 0, 0)
; DI float half_sum(float v) { auto rr = __builtin_amdgcn_permlane32_swap(__float_as_uint(v), __float_as_uint(v), false, false); return __uint_as_float(rr[0]) + __uint_as_float(rr[1]); }
; DI void attn_tile(LAS const unsigned char* Ks, LAS const unsigned char* VT, const bf16x8 (&qf)[4], int ql, int hi,
;                   bool need_mask, bool col_en, int lo_b, int hi_b, float& m_ref, float& l_run, f32x16 (&o)[2], f32x16 (&sp)[2]) {
;     ...
;         for (int ks = 0; ks < 4; ++ks) o[dh] = MFMA32(vf[ks], pk[ks >> 1][ks & 1], o[dh]);
; DI void attn_unit(LAS unsigned char* lds, const Args& a, int bg, int qt) {
;     ...
;         if (i == nsel) {
;             const float lt = half_sum(l_run); const float gi = GT[512] / lt;
; #pragma unroll
;             for (int r = 0; r < 16; ++r) { oacc[0][r] += gi * o[0][r]; oacc[1][r] += gi * o[1][r]; o[0][r] = 0.f; o[1][r] = 0.f; }
;             m_ref = 0.f; l_run = 0.f;
;         }
.Lat_cep_38:
	v_add_f32_e32 v141, v141, v118
	s_nop 1
	s_waitcnt lgkmcnt(0)
	v_mfma_f32_32x32x16_bf16 v[18:33], v[192:195], v[224:227], v[18:33]
	v_mfma_f32_32x32x16_bf16 v[2:17], v[208:211], v[224:227], v[2:17]
	v_mfma_f32_32x32x16_bf16 v[18:33], v[196:199], v[228:231], v[18:33]
	v_mfma_f32_32x32x16_bf16 v[2:17], v[212:215], v[228:231], v[2:17]
	v_mfma_f32_32x32x16_bf16 v[18:33], v[200:203], v[232:235], v[18:33]
	v_mfma_f32_32x32x16_bf16 v[2:17], v[216:219], v[232:235], v[2:17]
	v_mfma_f32_32x32x16_bf16 v[18:33], v[204:207], v[236:239], v[18:33]
	v_mfma_f32_32x32x16_bf16 v[2:17], v[220:223], v[236:239], v[2:17]
	s_cmp_eq_u32 s101, 0
	s_cbranch_scc0 .Lat_exit
	ds_read_b32 v131, v133 offset:2048
	v_mov_b32_e32 v130, v141
	v_mov_b32_e32 v129, v141
	s_nop 1
	v_permlane32_swap_b32_e32 v129, v130
	v_add_f32_e32 v129, v129, v130
	s_waitcnt lgkmcnt(0)
	v_div_scale_f32 v130, s[8:9], v129, v129, v131
	v_rcp_f32_e32 v132, v130
	v_div_scale_f32 v82, vcc, v131, v129, v131
	v_fma_f32 v83, -v130, v132, 1.0
	v_fmac_f32_e32 v132, v83, v132
	v_mul_f32_e32 v83, v82, v132
	v_fma_f32 v128, -v130, v83, v82
	v_fmac_f32_e32 v83, v128, v132
	v_fma_f32 v130, -v130, v83, v82
	v_div_fmas_f32 v130, v130, v132, v83
	v_div_fixup_f32 v117, v130, v129, v131
	s_nop 7
	v_fmac_f32_e32 v166, v117, v2
	v_fmac_f32_e32 v167, v117, v3
	v_fmac_f32_e32 v164, v117, v4
	v_fmac_f32_e32 v165, v117, v5
	v_fmac_f32_e32 v162, v117, v6
	v_fmac_f32_e32 v163, v117, v7
	v_fmac_f32_e32 v160, v117, v8
	v_fmac_f32_e32 v161, v117, v9
	v_fmac_f32_e32 v158, v117, v10
	v_fmac_f32_e32 v159, v117, v11
	v_fmac_f32_e32 v156, v117, v12
	v_fmac_f32_e32 v157, v117, v13
	v_fmac_f32_e32 v154, v117, v14
	v_fmac_f32_e32 v155, v117, v15
	v_fmac_f32_e32 v152, v117, v16
	v_fmac_f32_e32 v153, v117, v17
	v_fmac_f32_e32 v182, v117, v18
	v_fmac_f32_e32 v183, v117, v19
	v_fmac_f32_e32 v180, v117, v20
	v_fmac_f32_e32 v181, v117, v21
	v_fmac_f32_e32 v178, v117, v22
	v_fmac_f32_e32 v179, v117, v23
	v_fmac_f32_e32 v176, v117, v24
	v_fmac_f32_e32 v177, v117, v25
	v_fmac_f32_e32 v174, v117, v26
	v_fmac_f32_e32 v175, v117, v27
	v_fmac_f32_e32 v172, v117, v28
	v_fmac_f32_e32 v173, v117, v29
	v_fmac_f32_e32 v170, v117, v30
	v_fmac_f32_e32 v171, v117, v31
	v_fmac_f32_e32 v168, v117, v32
	v_fmac_f32_e32 v169, v117, v33
	v_mov_b32_e32 v18, 0
	v_mov_b32_e32 v2, 0
	v_mov_b32_e32 v19, 0
	v_mov_b32_e32 v3, 0
	v_mov_b32_e32 v20, 0
	v_mov_b32_e32 v4, 0
	v_mov_b32_e32 v21, 0
	v_mov_b32_e32 v5, 0
	v_mov_b32_e32 v22, 0
	v_mov_b32_e32 v6, 0
	v_mov_b32_e32 v23, 0
	v_mov_b32_e32 v7, 0
	v_mov_b32_e32 v24, 0
	v_mov_b32_e32 v8, 0
	v_mov_b32_e32 v25, 0
	v_mov_b32_e32 v9, 0
	v_mov_b32_e32 v26, 0
	v_mov_b32_e32 v10, 0
	v_mov_b32_e32 v27, 0
	v_mov_b32_e32 v11, 0
	v_mov_b32_e32 v28, 0
	v_mov_b32_e32 v12, 0
	v_mov_b32_e32 v29, 0
	v_mov_b32_e32 v13, 0
	v_mov_b32_e32 v30, 0
	v_mov_b32_e32 v14, 0
	v_mov_b32_e32 v31, 0
	v_mov_b32_e32 v15, 0
	v_mov_b32_e32 v32, 0
	v_mov_b32_e32 v16, 0
	v_mov_b32_e32 v33, 0
	v_mov_b32_e32 v17, 0
	v_mov_b32_e32 v141, 0
	v_mov_b32_e32 v143, 0
	s_mov_b32 s101, 1
	s_mov_b32 s100, s18
	s_add_i32 s67, s18, -3
	s_mov_b32 s68, 0
	s_branch .Lat_first
